# v070 + G_IN K-loop fully saddr-form (same scheme as G_DN): all six GEMM K-loops now issue every LDS-DMA piece as SGPR base + 32-bit VGPR offset with no per-iteration address VALU
# speedup vs baseline: 1.0025x; 1.0025x over previous
.LBB0_351:
	s_ashr_i32 s17, s16, 31
	s_lshl_b64 s[24:25], s[16:17], 20
	s_add_u32 s24, s10, s24
	s_addc_u32 s25, s34, s25
	s_and_b64 s[30:31], s[40:41], exec
	s_cselect_b32 s17, s25, s43
	s_cselect_b32 s18, s24, s42
	s_ashr_i32 s5, s4, 31
	s_lshl_b64 s[30:31], s[4:5], 20
	s_add_u32 s30, s26, s30
	s_addc_u32 s31, s27, s31
	s_and_b64 s[52:53], s[40:41], exec
	s_cselect_b32 s5, s31, s45
	s_cselect_b32 s20, s30, s44
	s_add_u32 s42, s42, 0x80080
	s_addc_u32 s43, s43, 0
	s_add_u32 s28, s44, 0x100
	v_mov_b32_e32 v0, 0
	s_addc_u32 s33, s45, 0
	s_mov_b32 s54, -2
	v_mov_b32_e32 v1, v0
	v_mov_b32_e32 v2, v0
	v_mov_b32_e32 v3, v0
	v_mov_b32_e32 v4, v0
	v_mov_b32_e32 v5, v0
	v_mov_b32_e32 v6, v0
	v_mov_b32_e32 v7, v0
	v_mov_b32_e32 v16, v0
	v_mov_b32_e32 v17, v0
	v_mov_b32_e32 v18, v0
	v_mov_b32_e32 v19, v0
	v_mov_b32_e32 v20, v0
	v_mov_b32_e32 v21, v0
	v_mov_b32_e32 v22, v0
	v_mov_b32_e32 v23, v0
	v_mov_b32_e32 v32, v0
	v_mov_b32_e32 v33, v0
	v_mov_b32_e32 v34, v0
	v_mov_b32_e32 v35, v0
	v_mov_b32_e32 v36, v0
	v_mov_b32_e32 v37, v0
	v_mov_b32_e32 v38, v0
	v_mov_b32_e32 v39, v0
	v_mov_b32_e32 v48, v0
	v_mov_b32_e32 v49, v0
	v_mov_b32_e32 v50, v0
	v_mov_b32_e32 v51, v0
	v_mov_b32_e32 v52, v0
	v_mov_b32_e32 v53, v0
	v_mov_b32_e32 v54, v0
	v_mov_b32_e32 v55, v0
	v_mov_b32_e32 v8, v0
	v_mov_b32_e32 v9, v0
	v_mov_b32_e32 v10, v0
	v_mov_b32_e32 v11, v0
	v_mov_b32_e32 v12, v0
	v_mov_b32_e32 v13, v0
	v_mov_b32_e32 v14, v0
	v_mov_b32_e32 v15, v0
	v_mov_b32_e32 v24, v0
	v_mov_b32_e32 v25, v0
	v_mov_b32_e32 v26, v0
	v_mov_b32_e32 v27, v0
	v_mov_b32_e32 v28, v0
	v_mov_b32_e32 v29, v0
	v_mov_b32_e32 v30, v0
	v_mov_b32_e32 v31, v0
	v_mov_b32_e32 v40, v0
	v_mov_b32_e32 v41, v0
	v_mov_b32_e32 v42, v0
	v_mov_b32_e32 v43, v0
	v_mov_b32_e32 v44, v0
	v_mov_b32_e32 v45, v0
	v_mov_b32_e32 v46, v0
	v_mov_b32_e32 v47, v0
	v_mov_b32_e32 v56, v0
	v_mov_b32_e32 v57, v0
	v_mov_b32_e32 v58, v0
	v_mov_b32_e32 v59, v0
	v_mov_b32_e32 v60, v0
	v_mov_b32_e32 v61, v0
	v_mov_b32_e32 v62, v0
	v_mov_b32_e32 v63, v0
	v_mov_b32_e32 v64, v0
	v_mov_b32_e32 v65, v0
	v_mov_b32_e32 v66, v0
	v_mov_b32_e32 v67, v0
	v_mov_b32_e32 v68, v0
	v_mov_b32_e32 v69, v0
	v_mov_b32_e32 v70, v0
	v_mov_b32_e32 v71, v0
	v_mov_b32_e32 v80, v0
	v_mov_b32_e32 v81, v0
	v_mov_b32_e32 v82, v0
	v_mov_b32_e32 v83, v0
	v_mov_b32_e32 v84, v0
	v_mov_b32_e32 v85, v0
	v_mov_b32_e32 v86, v0
	v_mov_b32_e32 v87, v0
	v_mov_b32_e32 v98, v0
	v_mov_b32_e32 v99, v0
	v_mov_b32_e32 v100, v0
	v_mov_b32_e32 v101, v0
	v_mov_b32_e32 v102, v0
	v_mov_b32_e32 v103, v0
	v_mov_b32_e32 v104, v0
	v_mov_b32_e32 v105, v0
	v_mov_b32_e32 v114, v0
	v_mov_b32_e32 v115, v0
	v_mov_b32_e32 v116, v0
	v_mov_b32_e32 v117, v0
	v_mov_b32_e32 v118, v0
	v_mov_b32_e32 v119, v0
	v_mov_b32_e32 v120, v0
	v_mov_b32_e32 v121, v0
	v_mov_b32_e32 v72, v0
	v_mov_b32_e32 v73, v0
	v_mov_b32_e32 v74, v0
	v_mov_b32_e32 v75, v0
	v_mov_b32_e32 v76, v0
	v_mov_b32_e32 v77, v0
	v_mov_b32_e32 v78, v0
	v_mov_b32_e32 v79, v0
	v_mov_b32_e32 v88, v0
	v_mov_b32_e32 v89, v0
	v_mov_b32_e32 v90, v0
	v_mov_b32_e32 v91, v0
	v_mov_b32_e32 v92, v0
	v_mov_b32_e32 v93, v0
	v_mov_b32_e32 v94, v0
	v_mov_b32_e32 v95, v0
	v_mov_b32_e32 v106, v0
	v_mov_b32_e32 v107, v0
	v_mov_b32_e32 v108, v0
	v_mov_b32_e32 v109, v0
	v_mov_b32_e32 v110, v0
	v_mov_b32_e32 v111, v0
	v_mov_b32_e32 v112, v0
	v_mov_b32_e32 v113, v0
	v_mov_b32_e32 v122, v0
	v_mov_b32_e32 v123, v0
	v_mov_b32_e32 v124, v0
	v_mov_b32_e32 v125, v0
	v_mov_b32_e32 v126, v0
	v_mov_b32_e32 v127, v0
	v_mov_b32_e32 v128, v0
	v_mov_b32_e32 v129, v0
	v_add_u32_e32 v154, 0x80, v142
	v_add_u32_e32 v155, 0x80, v138
	v_add_u32_e32 v156, 0x80, v144
	v_add_u32_e32 v157, 0x80, v140
	v_add_u32_e32 v202, 0x80000, v144
	v_add_u32_e32 v203, 0x80000, v140

.Lrx_G_IN_0:
	s_waitcnt vmcnt(16)
	s_waitcnt lgkmcnt(0)
	s_setprio 1
	s_barrier
	v_mfma_f32_16x16x32_bf16 v[126:129], v[130:133], v[188:191], v[126:129]
	v_mfma_f32_16x16x32_bf16 v[122:125], v[164:167], v[188:191], v[122:125]
	v_mfma_f32_16x16x32_bf16 v[110:113], v[130:133], v[196:199], v[110:113]
	v_mfma_f32_16x16x32_bf16 v[106:109], v[164:167], v[196:199], v[106:109]
	v_mfma_f32_16x16x32_bf16 v[92:95], v[130:133], v[214:217], v[92:95]
	v_mfma_f32_16x16x32_bf16 v[88:91], v[164:167], v[214:217], v[88:91]
	v_mfma_f32_16x16x32_bf16 v[76:79], v[130:133], v[222:225], v[76:79]
	v_mfma_f32_16x16x32_bf16 v[72:75], v[164:167], v[222:225], v[72:75]
	v_mfma_f32_16x16x32_bf16 v[126:129], v[160:163], v[192:195], v[126:129]
	v_mfma_f32_16x16x32_bf16 v[122:125], v[168:171], v[192:195], v[122:125]
	v_mfma_f32_16x16x32_bf16 v[110:113], v[160:163], v[210:213], v[110:113]
	v_mfma_f32_16x16x32_bf16 v[106:109], v[168:171], v[210:213], v[106:109]
	v_mfma_f32_16x16x32_bf16 v[92:95], v[160:163], v[218:221], v[92:95]
	v_mfma_f32_16x16x32_bf16 v[88:91], v[168:171], v[218:221], v[88:91]
	v_mfma_f32_16x16x32_bf16 v[76:79], v[160:163], v[226:229], v[76:79]
	v_mfma_f32_16x16x32_bf16 v[72:75], v[168:171], v[226:229], v[72:75]
	v_mfma_f32_16x16x32_bf16 v[118:121], v[172:175], v[188:191], v[118:121]
	v_mfma_f32_16x16x32_bf16 v[114:117], v[180:183], v[188:191], v[114:117]
	v_mfma_f32_16x16x32_bf16 v[102:105], v[172:175], v[196:199], v[102:105]
	v_mfma_f32_16x16x32_bf16 v[98:101], v[180:183], v[196:199], v[98:101]
	v_mfma_f32_16x16x32_bf16 v[84:87], v[172:175], v[214:217], v[84:87]
	v_mfma_f32_16x16x32_bf16 v[80:83], v[180:183], v[214:217], v[80:83]
	v_mfma_f32_16x16x32_bf16 v[68:71], v[172:175], v[222:225], v[68:71]
	v_mfma_f32_16x16x32_bf16 v[64:67], v[180:183], v[222:225], v[64:67]
	v_mfma_f32_16x16x32_bf16 v[118:121], v[176:179], v[192:195], v[118:121]
	v_mfma_f32_16x16x32_bf16 v[114:117], v[184:187], v[192:195], v[114:117]
	v_mfma_f32_16x16x32_bf16 v[102:105], v[176:179], v[210:213], v[102:105]
	v_mfma_f32_16x16x32_bf16 v[98:101], v[184:187], v[210:213], v[98:101]
	v_mfma_f32_16x16x32_bf16 v[84:87], v[176:179], v[218:221], v[84:87]
	v_mfma_f32_16x16x32_bf16 v[80:83], v[184:187], v[218:221], v[80:83]
	v_mfma_f32_16x16x32_bf16 v[68:71], v[176:179], v[226:229], v[68:71]
	v_mfma_f32_16x16x32_bf16 v[64:67], v[184:187], v[226:229], v[64:67]
	s_barrier
	s_setprio 0
	s_add_i32 s55, s55, s75
	s_mov_b32 m0, s55
	ds_read_b128 v[188:191], v159 offset:16384
	ds_read_b128 v[192:195], v159 offset:17408
	ds_read_b128 v[196:199], v159 offset:18432
	ds_read_b128 v[210:213], v159 offset:19456
	ds_read_b128 v[214:217], v159 offset:20480
	ds_read_b128 v[218:221], v159 offset:21504
	ds_read_b128 v[222:225], v159 offset:22528
	ds_read_b128 v[226:229], v159 offset:23552
	global_load_lds_dwordx4 v142, s[44:45]
	s_add_i32 m0, s55, 0x2000
	s_add_u32 s56, s44, 0x80000
	s_addc_u32 s57, s45, 0
	s_add_i32 s55, s61, s75
	global_load_lds_dwordx4 v138, s[44:45]
	s_mov_b32 m0, s55
	s_nop 0
	global_load_lds_dwordx4 v142, s[56:57]
	s_add_i32 m0, s55, 0x2000
	s_nop 0
	global_load_lds_dwordx4 v138, s[56:57]
	s_mov_b32 m0, s35
	s_nop 0
	global_load_lds_dwordx4 v144, s[52:53]
	s_mov_b32 m0, s68
	s_nop 0
	global_load_lds_dwordx4 v140, s[52:53]
	v_cmp_ne_u32_e32 vcc, 0, v243
	s_cbranch_vccnz .Lrx_G_IN_1
	s_waitcnt vmcnt(8)
.Lrx_G_IN_1:
	s_waitcnt vmcnt(16)
	v_mov_b32_e32 v243, 0
	s_waitcnt lgkmcnt(0)
	s_setprio 1
	s_barrier
	v_mfma_f32_16x16x32_bf16 v[60:63], v[130:133], v[188:191], v[60:63]
	v_mfma_f32_16x16x32_bf16 v[56:59], v[164:167], v[188:191], v[56:59]
	v_mfma_f32_16x16x32_bf16 v[44:47], v[130:133], v[196:199], v[44:47]
	v_mfma_f32_16x16x32_bf16 v[40:43], v[164:167], v[196:199], v[40:43]
	v_mfma_f32_16x16x32_bf16 v[28:31], v[130:133], v[214:217], v[28:31]
	v_mfma_f32_16x16x32_bf16 v[24:27], v[164:167], v[214:217], v[24:27]
	v_mfma_f32_16x16x32_bf16 v[12:15], v[130:133], v[222:225], v[12:15]
	v_mfma_f32_16x16x32_bf16 v[8:11], v[164:167], v[222:225], v[8:11]
	v_mfma_f32_16x16x32_bf16 v[60:63], v[160:163], v[192:195], v[60:63]
	v_mfma_f32_16x16x32_bf16 v[56:59], v[168:171], v[192:195], v[56:59]
	v_mfma_f32_16x16x32_bf16 v[44:47], v[160:163], v[210:213], v[44:47]
	v_mfma_f32_16x16x32_bf16 v[40:43], v[168:171], v[210:213], v[40:43]
	v_mfma_f32_16x16x32_bf16 v[28:31], v[160:163], v[218:221], v[28:31]
	v_mfma_f32_16x16x32_bf16 v[24:27], v[168:171], v[218:221], v[24:27]
	v_mfma_f32_16x16x32_bf16 v[12:15], v[160:163], v[226:229], v[12:15]
	v_mfma_f32_16x16x32_bf16 v[8:11], v[168:171], v[226:229], v[8:11]
	v_mfma_f32_16x16x32_bf16 v[52:55], v[172:175], v[188:191], v[52:55]
	v_mfma_f32_16x16x32_bf16 v[48:51], v[180:183], v[188:191], v[48:51]
	v_mfma_f32_16x16x32_bf16 v[36:39], v[172:175], v[196:199], v[36:39]
	v_mfma_f32_16x16x32_bf16 v[32:35], v[180:183], v[196:199], v[32:35]
	v_mfma_f32_16x16x32_bf16 v[20:23], v[172:175], v[214:217], v[20:23]
	v_mfma_f32_16x16x32_bf16 v[16:19], v[180:183], v[214:217], v[16:19]
	v_mfma_f32_16x16x32_bf16 v[4:7], v[172:175], v[222:225], v[4:7]
	v_mfma_f32_16x16x32_bf16 v[0:3], v[180:183], v[222:225], v[0:3]
	v_mfma_f32_16x16x32_bf16 v[52:55], v[176:179], v[192:195], v[52:55]
	v_mfma_f32_16x16x32_bf16 v[48:51], v[184:187], v[192:195], v[48:51]
	v_mfma_f32_16x16x32_bf16 v[36:39], v[176:179], v[210:213], v[36:39]
	v_mfma_f32_16x16x32_bf16 v[32:35], v[184:187], v[210:213], v[32:35]
	v_mfma_f32_16x16x32_bf16 v[20:23], v[176:179], v[218:221], v[20:23]
	v_mfma_f32_16x16x32_bf16 v[16:19], v[184:187], v[218:221], v[16:19]
	v_mfma_f32_16x16x32_bf16 v[4:7], v[176:179], v[226:229], v[4:7]
	v_mfma_f32_16x16x32_bf16 v[0:3], v[184:187], v[226:229], v[0:3]
	s_barrier
	s_setprio 0
	s_add_i32 s55, 0, 0x18000
	s_add_i32 s56, 0, 0x1c000
	v_add_u32_e32 v168, s55, v158
	v_add_u32_e32 v184, s56, v158
	ds_read_b128 v[130:133], v168
	ds_read_b128 v[160:163], v168 offset:1024
	ds_read_b128 v[164:167], v168 offset:2048
	ds_read_b128 v[168:171], v168 offset:3072
	ds_read_b128 v[172:175], v184
	ds_read_b128 v[176:179], v184 offset:1024
	ds_read_b128 v[180:183], v184 offset:2048
	ds_read_b128 v[184:187], v184 offset:3072
	s_mov_b32 m0, s69
	ds_read_b128 v[188:191], v159 offset:32768
	ds_read_b128 v[192:195], v159 offset:33792
	ds_read_b128 v[196:199], v159 offset:34816
	ds_read_b128 v[210:213], v159 offset:35840
	ds_read_b128 v[214:217], v159 offset:36864
	ds_read_b128 v[218:221], v159 offset:37888
	ds_read_b128 v[222:225], v159 offset:38912
	ds_read_b128 v[226:229], v159 offset:39936
	global_load_lds_dwordx4 v202, s[52:53]
	s_mov_b32 m0, s77
	s_nop 0
	global_load_lds_dwordx4 v203, s[52:53]
	s_waitcnt vmcnt(8)
	s_waitcnt lgkmcnt(0)
	s_setprio 1
	s_barrier
	v_mfma_f32_16x16x32_bf16 v[126:129], v[130:133], v[188:191], v[126:129]
	v_mfma_f32_16x16x32_bf16 v[122:125], v[164:167], v[188:191], v[122:125]
	v_mfma_f32_16x16x32_bf16 v[110:113], v[130:133], v[196:199], v[110:113]
	v_mfma_f32_16x16x32_bf16 v[106:109], v[164:167], v[196:199], v[106:109]
	v_mfma_f32_16x16x32_bf16 v[92:95], v[130:133], v[214:217], v[92:95]
	v_mfma_f32_16x16x32_bf16 v[88:91], v[164:167], v[214:217], v[88:91]
	v_mfma_f32_16x16x32_bf16 v[76:79], v[130:133], v[222:225], v[76:79]
	v_mfma_f32_16x16x32_bf16 v[72:75], v[164:167], v[222:225], v[72:75]
	v_mfma_f32_16x16x32_bf16 v[126:129], v[160:163], v[192:195], v[126:129]
	v_mfma_f32_16x16x32_bf16 v[122:125], v[168:171], v[192:195], v[122:125]
	v_mfma_f32_16x16x32_bf16 v[110:113], v[160:163], v[210:213], v[110:113]
	v_mfma_f32_16x16x32_bf16 v[106:109], v[168:171], v[210:213], v[106:109]
	v_mfma_f32_16x16x32_bf16 v[92:95], v[160:163], v[218:221], v[92:95]
	v_mfma_f32_16x16x32_bf16 v[88:91], v[168:171], v[218:221], v[88:91]
	v_mfma_f32_16x16x32_bf16 v[76:79], v[160:163], v[226:229], v[76:79]
	v_mfma_f32_16x16x32_bf16 v[72:75], v[168:171], v[226:229], v[72:75]
	v_mfma_f32_16x16x32_bf16 v[118:121], v[172:175], v[188:191], v[118:121]
	v_mfma_f32_16x16x32_bf16 v[114:117], v[180:183], v[188:191], v[114:117]
	v_mfma_f32_16x16x32_bf16 v[102:105], v[172:175], v[196:199], v[102:105]
	v_mfma_f32_16x16x32_bf16 v[98:101], v[180:183], v[196:199], v[98:101]
	v_mfma_f32_16x16x32_bf16 v[84:87], v[172:175], v[214:217], v[84:87]
	v_mfma_f32_16x16x32_bf16 v[80:83], v[180:183], v[214:217], v[80:83]
	v_mfma_f32_16x16x32_bf16 v[68:71], v[172:175], v[222:225], v[68:71]
	v_mfma_f32_16x16x32_bf16 v[64:67], v[180:183], v[222:225], v[64:67]
	v_mfma_f32_16x16x32_bf16 v[118:121], v[176:179], v[192:195], v[118:121]
	v_mfma_f32_16x16x32_bf16 v[114:117], v[184:187], v[192:195], v[114:117]
	v_mfma_f32_16x16x32_bf16 v[102:105], v[176:179], v[210:213], v[102:105]
	v_mfma_f32_16x16x32_bf16 v[98:101], v[184:187], v[210:213], v[98:101]
	v_mfma_f32_16x16x32_bf16 v[84:87], v[176:179], v[218:221], v[84:87]
	v_mfma_f32_16x16x32_bf16 v[80:83], v[184:187], v[218:221], v[80:83]
	v_mfma_f32_16x16x32_bf16 v[68:71], v[176:179], v[226:229], v[68:71]
	v_mfma_f32_16x16x32_bf16 v[64:67], v[184:187], v[226:229], v[64:67]
	s_barrier
	s_setprio 0
	s_add_i32 s57, s55, s75
	s_mov_b32 m0, s57
	ds_read_b128 v[188:191], v159 offset:49152
	ds_read_b128 v[192:195], v159 offset:50176
	ds_read_b128 v[196:199], v159 offset:51200
	ds_read_b128 v[210:213], v159 offset:52224
	ds_read_b128 v[214:217], v159 offset:53248
	ds_read_b128 v[218:221], v159 offset:54272
	ds_read_b128 v[222:225], v159 offset:55296
	ds_read_b128 v[226:229], v159 offset:56320
	global_load_lds_dwordx4 v154, s[44:45]
	s_add_i32 m0, s57, 0x2000
	s_add_i32 s57, s56, s75
	global_load_lds_dwordx4 v155, s[44:45]
	s_add_u32 s44, s44, 0x80080
	s_addc_u32 s45, s45, 0
	s_mov_b32 m0, s57
	s_nop 0
	global_load_lds_dwordx4 v142, s[44:45]
	s_add_i32 m0, s57, 0x2000
	s_nop 0
	global_load_lds_dwordx4 v138, s[44:45]
	s_mov_b32 m0, s79
	s_nop 0
	global_load_lds_dwordx4 v156, s[52:53]
	s_mov_b32 m0, s81
	s_nop 0
	global_load_lds_dwordx4 v157, s[52:53]
	s_waitcnt vmcnt(8)
	s_waitcnt lgkmcnt(0)
	s_setprio 1
	s_barrier
	v_mfma_f32_16x16x32_bf16 v[60:63], v[130:133], v[188:191], v[60:63]
	v_mfma_f32_16x16x32_bf16 v[56:59], v[164:167], v[188:191], v[56:59]
	v_mfma_f32_16x16x32_bf16 v[44:47], v[130:133], v[196:199], v[44:47]
	v_mfma_f32_16x16x32_bf16 v[40:43], v[164:167], v[196:199], v[40:43]
	v_mfma_f32_16x16x32_bf16 v[28:31], v[130:133], v[214:217], v[28:31]
	v_mfma_f32_16x16x32_bf16 v[24:27], v[164:167], v[214:217], v[24:27]
	v_mfma_f32_16x16x32_bf16 v[12:15], v[130:133], v[222:225], v[12:15]
	v_mfma_f32_16x16x32_bf16 v[8:11], v[164:167], v[222:225], v[8:11]
	v_mfma_f32_16x16x32_bf16 v[60:63], v[160:163], v[192:195], v[60:63]
	v_mfma_f32_16x16x32_bf16 v[56:59], v[168:171], v[192:195], v[56:59]
	v_mfma_f32_16x16x32_bf16 v[44:47], v[160:163], v[210:213], v[44:47]
	v_mfma_f32_16x16x32_bf16 v[40:43], v[168:171], v[210:213], v[40:43]
	v_mfma_f32_16x16x32_bf16 v[28:31], v[160:163], v[218:221], v[28:31]
	v_mfma_f32_16x16x32_bf16 v[24:27], v[168:171], v[218:221], v[24:27]
	v_mfma_f32_16x16x32_bf16 v[12:15], v[160:163], v[226:229], v[12:15]
	v_mfma_f32_16x16x32_bf16 v[8:11], v[168:171], v[226:229], v[8:11]
	v_mfma_f32_16x16x32_bf16 v[52:55], v[172:175], v[188:191], v[52:55]
	v_mfma_f32_16x16x32_bf16 v[48:51], v[180:183], v[188:191], v[48:51]
	v_mfma_f32_16x16x32_bf16 v[36:39], v[172:175], v[196:199], v[36:39]
	v_mfma_f32_16x16x32_bf16 v[32:35], v[180:183], v[196:199], v[32:35]
	v_mfma_f32_16x16x32_bf16 v[20:23], v[172:175], v[214:217], v[20:23]
	v_mfma_f32_16x16x32_bf16 v[16:19], v[180:183], v[214:217], v[16:19]
	v_mfma_f32_16x16x32_bf16 v[4:7], v[172:175], v[222:225], v[4:7]
	v_mfma_f32_16x16x32_bf16 v[0:3], v[180:183], v[222:225], v[0:3]
	v_mfma_f32_16x16x32_bf16 v[52:55], v[176:179], v[192:195], v[52:55]
	v_mfma_f32_16x16x32_bf16 v[48:51], v[184:187], v[192:195], v[48:51]
	v_mfma_f32_16x16x32_bf16 v[36:39], v[176:179], v[210:213], v[36:39]
	v_mfma_f32_16x16x32_bf16 v[32:35], v[184:187], v[210:213], v[32:35]
	v_mfma_f32_16x16x32_bf16 v[20:23], v[176:179], v[218:221], v[20:23]
	v_mfma_f32_16x16x32_bf16 v[16:19], v[184:187], v[218:221], v[16:19]
	v_mfma_f32_16x16x32_bf16 v[4:7], v[176:179], v[226:229], v[4:7]
	v_mfma_f32_16x16x32_bf16 v[0:3], v[184:187], v[226:229], v[0:3]
	s_barrier
	s_setprio 0
	s_add_i32 s54, s54, 2
	s_add_u32 s42, s42, 0x100
	s_addc_u32 s43, s43, 0
	s_add_u32 s28, s28, 0x100
	s_addc_u32 s33, s33, 0
	s_cmp_gt_u32 s54, 29
	s_cbranch_scc0 .LBB0_352
	v_mov_b32_e32 v243, 1
	v_readlane_b32 s6, v251, 54
	v_readlane_b32 s7, v251, 55
	s_and_b64 vcc, exec, s[6:7]
	s_cbranch_vccz .LBB0_355
	s_barrier
